# EpiRes epilogues: first-half loads batched, second-half loads hoisted above the last row step of the first half (on top of QKV batching)
# baseline (speedup 1.0000x reference)
;     __device__ __forceinline__ void operator()(const f32x4 (&acc)[2][2][4][2], const Unit& u, int wr, int wc, int fr, int fq) const {
;     ...
;             for (int m = 0; m < 4; ++m) {
;                 const int row = row0 + ai * HALF + m * 16; const size_t off = (size_t)row * 1024 + col0;
;                 ra[m] = 1.0f; rmu[m] = 0.0f;
;                 if (st) {
;                     const f32x2v sv = *(const f32x2v*)(st + 2 * (size_t)row); rmu[m] = sv.x * (1.0f / 1024.0f); ra[m] = rsqrtf(sv.y * (1.0f / 1024.0f) - rmu[m] * rmu[m] + 1e-5f);
;                     hv[m][0] = *(const f16x8*)(yh + off); hv[m][1] = *(const f16x8*)(yh + off + 32);
;                 }
;             }
.LBB0_429:
	v_lshl_add_u32 v228, s9, 8, v210
	v_lshl_add_u64 v[226:227], v[224:225], 1, s[92:93]
	v_ashrrev_i32_e32 v229, 31, v228
	v_or_b32_e32 v240, 16, v228
	v_ashrrev_i32_e32 v241, 31, v240
	v_or_b32_e32 v234, 32, v228
	v_ashrrev_i32_e32 v235, 31, v234
	v_or_b32_e32 v230, 48, v228
	v_ashrrev_i32_e32 v231, 31, v230
	v_mov_b32_e32 v242, 1.0
	v_mov_b32_e32 v244, 1.0
	v_mov_b32_e32 v237, 1.0
	v_mov_b32_e32 v232, 1.0
	v_mov_b32_e32 v178, 0
	v_mov_b32_e32 v179, s77
	v_mov_b32_e32 v180, s77
	v_mov_b32_e32 v181, s77
	s_and_b64 vcc, exec, s[38:39]
	s_cbranch_vccnz .Lres0_h1_nost
	v_lshl_add_u64 v[198:199], v[228:229], 3, s[50:51]
	global_load_dwordx2 v[246:247], v[198:199], off
	global_load_dwordx2 v[248:249], v[198:199], off offset:128
	global_load_dwordx2 v[250:251], v[198:199], off offset:256
	global_load_dwordx2 v[238:239], v[198:199], off offset:384
	v_lshlrev_b64 v[200:201], 11, v[228:229]
	v_lshl_add_u64 v[200:201], v[226:227], 0, v[200:201]
	global_load_dwordx4 v[158:161], v[200:201], off
	global_load_dwordx4 v[146:149], v[200:201], off offset:64
	v_lshlrev_b64 v[200:201], 11, v[240:241]
	v_lshl_add_u64 v[200:201], v[226:227], 0, v[200:201]
	global_load_dwordx4 v[138:141], v[200:201], off
	global_load_dwordx4 v[130:133], v[200:201], off offset:64
	v_lshlrev_b64 v[200:201], 11, v[234:235]
	v_lshl_add_u64 v[200:201], v[226:227], 0, v[200:201]
	global_load_dwordx4 v[118:121], v[200:201], off
	global_load_dwordx4 v[106:109], v[200:201], off offset:64
	v_lshlrev_b64 v[200:201], 11, v[230:231]
	v_lshl_add_u64 v[200:201], v[226:227], 0, v[200:201]
	global_load_dwordx4 v[102:105], v[200:201], off
	global_load_dwordx4 v[98:101], v[200:201], off offset:64
	s_waitcnt vmcnt(0)
	v_pk_mul_f32 v[246:247], v[246:247], s[64:65] op_sel_hi:[1,0]
	s_nop 0
	v_fma_f32 v247, -v246, v246, v247
	v_add_f32_e32 v247, 0x3727c5ac, v247
	v_mul_f32_e32 v236, 0x4b800000, v247
	v_cmp_gt_f32_e32 vcc, s29, v247
	v_mov_b32_e32 v178, v246
	s_nop 0
	v_cndmask_b32_e32 v247, v247, v236, vcc
	v_rsq_f32_e32 v247, v247
	s_nop 0
	v_mul_f32_e32 v236, 0x45800000, v247
	v_cndmask_b32_e32 v242, v247, v236, vcc
	v_pk_mul_f32 v[248:249], v[248:249], s[64:65] op_sel_hi:[1,0]
	s_nop 0
	v_fma_f32 v249, -v248, v248, v249
	v_add_f32_e32 v249, 0x3727c5ac, v249
	v_mul_f32_e32 v236, 0x4b800000, v249
	v_cmp_gt_f32_e32 vcc, s29, v249
	v_mov_b32_e32 v179, v248
	s_nop 0
	v_cndmask_b32_e32 v249, v249, v236, vcc
	v_rsq_f32_e32 v249, v249
	s_nop 0
	v_mul_f32_e32 v236, 0x45800000, v249
	v_cndmask_b32_e32 v244, v249, v236, vcc
	v_pk_mul_f32 v[250:251], v[250:251], s[64:65] op_sel_hi:[1,0]
	s_nop 0
	v_fma_f32 v251, -v250, v250, v251
	v_add_f32_e32 v251, 0x3727c5ac, v251
	v_mul_f32_e32 v236, 0x4b800000, v251
	v_cmp_gt_f32_e32 vcc, s29, v251
	v_mov_b32_e32 v180, v250
	s_nop 0
	v_cndmask_b32_e32 v251, v251, v236, vcc
	v_rsq_f32_e32 v251, v251
	s_nop 0
	v_mul_f32_e32 v236, 0x45800000, v251
	v_cndmask_b32_e32 v237, v251, v236, vcc
	v_pk_mul_f32 v[238:239], v[238:239], s[64:65] op_sel_hi:[1,0]
	s_nop 0
	v_fma_f32 v239, -v238, v238, v239
	v_add_f32_e32 v239, 0x3727c5ac, v239
	v_mul_f32_e32 v236, 0x4b800000, v239
	v_cmp_gt_f32_e32 vcc, s29, v239
	v_mov_b32_e32 v181, v238
	s_nop 0
	v_cndmask_b32_e32 v239, v239, v236, vcc
	v_rsq_f32_e32 v239, v239
	s_nop 0
	v_mul_f32_e32 v236, 0x45800000, v239
	v_cndmask_b32_e32 v232, v239, v236, vcc

;     __device__ __forceinline__ void operator()(const f32x4 (&acc)[2][2][4][2], const Unit& u, int wr, int wc, int fr, int fq) const {
;     ...
;             for (int m = 0; m < 4; ++m) {
;                 const int row = row0 + ai * HALF + m * 16; const size_t off = (size_t)row * 1024 + col0;
;                 ra[m] = 1.0f; rmu[m] = 0.0f;
;                 if (st) {
;                     const f32x2v sv = *(const f32x2v*)(st + 2 * (size_t)row); rmu[m] = sv.x * (1.0f / 1024.0f); ra[m] = rsqrtf(sv.y * (1.0f / 1024.0f) - rmu[m] * rmu[m] + 1e-5f);
;                     hv[m][0] = *(const f16x8*)(yh + off); hv[m][1] = *(const f16x8*)(yh + off + 32);
;                 }
;             }
.LBB0_474:
	s_and_b64 vcc, exec, s[38:39]
	s_cbranch_vccnz .Lres0_h2_skip
	v_add_u32_e32 v162, 0x80, v228
	v_ashrrev_i32_e32 v163, 31, v162
	v_lshl_add_u64 v[164:165], v[162:163], 3, s[50:51]
	global_load_dwordx2 v[166:167], v[164:165], off
	global_load_dwordx2 v[168:169], v[164:165], off offset:128
	global_load_dwordx2 v[170:171], v[164:165], off offset:256
	global_load_dwordx2 v[172:173], v[164:165], off offset:384
	v_add_u32_e32 v162, 0x80, v228
	v_ashrrev_i32_e32 v163, 31, v162
	v_lshlrev_b64 v[164:165], 11, v[162:163]
	v_lshl_add_u64 v[164:165], v[226:227], 0, v[164:165]
	global_load_dwordx4 v[158:161], v[164:165], off
	global_load_dwordx4 v[146:149], v[164:165], off offset:64
	v_add_u32_e32 v162, 0x90, v228
	v_ashrrev_i32_e32 v163, 31, v162
	v_lshlrev_b64 v[164:165], 11, v[162:163]
	v_lshl_add_u64 v[164:165], v[226:227], 0, v[164:165]
	global_load_dwordx4 v[138:141], v[164:165], off
	global_load_dwordx4 v[130:133], v[164:165], off offset:64
	v_add_u32_e32 v162, 0xa0, v228
	v_ashrrev_i32_e32 v163, 31, v162
	v_lshlrev_b64 v[164:165], 11, v[162:163]
	v_lshl_add_u64 v[164:165], v[226:227], 0, v[164:165]
	global_load_dwordx4 v[118:121], v[164:165], off
	global_load_dwordx4 v[106:109], v[164:165], off offset:64
	v_add_u32_e32 v162, 0xb0, v228
	v_ashrrev_i32_e32 v163, 31, v162
	v_lshlrev_b64 v[164:165], 11, v[162:163]
	v_lshl_add_u64 v[164:165], v[226:227], 0, v[164:165]
	global_load_dwordx4 v[102:105], v[164:165], off
	global_load_dwordx4 v[98:101], v[164:165], off offset:64

;     __device__ __forceinline__ void operator()(const f32x4 (&acc)[2][2][4][2], const Unit& u, int wr, int wc, int fr, int fq) const {
;     ...
;             for (int m = 0; m < 4; ++m) {
;                 const int row = row0 + ai * HALF + m * 16; const size_t off = (size_t)row * 1024 + col0;
;                 ra[m] = 1.0f; rmu[m] = 0.0f;
;                 if (st) {
;                     const f32x2v sv = *(const f32x2v*)(st + 2 * (size_t)row); rmu[m] = sv.x * (1.0f / 1024.0f); ra[m] = rsqrtf(sv.y * (1.0f / 1024.0f) - rmu[m] * rmu[m] + 1e-5f);
.LBB0_478:
	s_or_b64 exec, exec, s[36:37]
	v_add_u32_e32 v150, 0x80, v228
	v_ashrrev_i32_e32 v151, 31, v150
	v_add_u32_e32 v136, 0x90, v228
	v_ashrrev_i32_e32 v137, 31, v136
	v_add_u32_e32 v128, 0xa0, v228
	v_ashrrev_i32_e32 v129, 31, v128
	v_add_u32_e32 v116, 0xb0, v228
	v_ashrrev_i32_e32 v117, 31, v116
	s_waitcnt lgkmcnt(0)
	v_mov_b32_e32 v144, s2
	v_mov_b32_e32 v145, s2
	v_mov_b32_e32 v126, s2
	v_mov_b32_e32 v127, s2
	v_mov_b32_e32 v152, 0
	v_mov_b32_e32 v142, 0
	v_mov_b32_e32 v134, 0
	v_mov_b32_e32 v110, 0
	s_and_b64 vcc, exec, s[38:39]
	s_cbranch_vccnz .Lres0_h2_nost
	s_waitcnt vmcnt(3)
	v_pk_mul_f32 v[166:167], v[166:167], s[64:65] op_sel_hi:[1,0]
	s_nop 0
	v_fma_f32 v167, -v166, v166, v167
	v_add_f32_e32 v167, 0x3727c5ac, v167
	v_mul_f32_e32 v174, 0x4b800000, v167
	v_cmp_gt_f32_e32 vcc, s29, v167
	v_mov_b32_e32 v152, v166
	s_nop 0
	v_cndmask_b32_e32 v167, v167, v174, vcc
	v_rsq_f32_e32 v167, v167
	s_nop 0
	v_mul_f32_e32 v174, 0x45800000, v167
	v_cndmask_b32_e32 v144, v167, v174, vcc
	v_pk_mul_f32 v[168:169], v[168:169], s[64:65] op_sel_hi:[1,0]
	s_nop 0
	v_fma_f32 v169, -v168, v168, v169
	v_add_f32_e32 v169, 0x3727c5ac, v169
	v_mul_f32_e32 v174, 0x4b800000, v169
	v_cmp_gt_f32_e32 vcc, s29, v169
	v_mov_b32_e32 v142, v168
	s_nop 0
	v_cndmask_b32_e32 v169, v169, v174, vcc
	v_rsq_f32_e32 v169, v169
	s_nop 0
	v_mul_f32_e32 v174, 0x45800000, v169
	v_cndmask_b32_e32 v145, v169, v174, vcc
	v_pk_mul_f32 v[170:171], v[170:171], s[64:65] op_sel_hi:[1,0]
	s_nop 0
	v_fma_f32 v171, -v170, v170, v171
	v_add_f32_e32 v171, 0x3727c5ac, v171
	v_mul_f32_e32 v174, 0x4b800000, v171
	v_cmp_gt_f32_e32 vcc, s29, v171
	v_mov_b32_e32 v134, v170
	s_nop 0
	v_cndmask_b32_e32 v171, v171, v174, vcc
	v_rsq_f32_e32 v171, v171
	s_nop 0
	v_mul_f32_e32 v174, 0x45800000, v171
	v_cndmask_b32_e32 v126, v171, v174, vcc
	v_pk_mul_f32 v[172:173], v[172:173], s[64:65] op_sel_hi:[1,0]
	s_nop 0
	v_fma_f32 v173, -v172, v172, v173
	v_add_f32_e32 v173, 0x3727c5ac, v173
	v_mul_f32_e32 v174, 0x4b800000, v173
	v_cmp_gt_f32_e32 vcc, s29, v173
	v_mov_b32_e32 v110, v172
	s_nop 0
	v_cndmask_b32_e32 v173, v173, v174, vcc
	v_rsq_f32_e32 v173, v173
	s_nop 0
	v_mul_f32_e32 v174, 0x45800000, v173
	v_cndmask_b32_e32 v127, v173, v174, vcc

;     __device__ __forceinline__ void operator()(const f32x4 (&acc)[2][2][4][2], const Unit& u, int wr, int wc, int fr, int fq) const {
;     ...
;             for (int m = 0; m < 4; ++m) {
;                 const int row = row0 + ai * HALF + m * 16; const size_t off = (size_t)row * 1024 + col0;
;                 ra[m] = 1.0f; rmu[m] = 0.0f;
;                 if (st) {
;                     const f32x2v sv = *(const f32x2v*)(st + 2 * (size_t)row); rmu[m] = sv.x * (1.0f / 1024.0f); ra[m] = rsqrtf(sv.y * (1.0f / 1024.0f) - rmu[m] * rmu[m] + 1e-5f);
;                     hv[m][0] = *(const f16x8*)(yh + off); hv[m][1] = *(const f16x8*)(yh + off + 32);
;                 }
;             }
.LBB0_870:
	v_lshl_add_u32 v228, s8, 8, v210
	v_lshl_add_u64 v[226:227], v[224:225], 1, s[92:93]
	v_ashrrev_i32_e32 v229, 31, v228
	v_or_b32_e32 v240, 16, v228
	v_ashrrev_i32_e32 v241, 31, v240
	v_or_b32_e32 v234, 32, v228
	v_ashrrev_i32_e32 v235, 31, v234
	v_or_b32_e32 v230, 48, v228
	v_ashrrev_i32_e32 v231, 31, v230
	v_mov_b32_e32 v244, 1.0
	v_mov_b32_e32 v242, 1.0
	v_mov_b32_e32 v237, 1.0
	v_mov_b32_e32 v232, 1.0
	v_mov_b32_e32 v178, 0
	v_mov_b32_e32 v179, s77
	v_mov_b32_e32 v180, s77
	v_mov_b32_e32 v181, s77
	s_and_b64 vcc, exec, s[38:39]
	s_cbranch_vccnz .Lres1_h1_nost
	v_lshl_add_u64 v[198:199], v[228:229], 3, s[80:81]
	global_load_dwordx2 v[246:247], v[198:199], off
	global_load_dwordx2 v[248:249], v[198:199], off offset:128
	global_load_dwordx2 v[250:251], v[198:199], off offset:256
	global_load_dwordx2 v[238:239], v[198:199], off offset:384
	v_lshlrev_b64 v[200:201], 11, v[228:229]
	v_lshl_add_u64 v[200:201], v[226:227], 0, v[200:201]
	global_load_dwordx4 v[158:161], v[200:201], off
	global_load_dwordx4 v[146:149], v[200:201], off offset:64
	v_lshlrev_b64 v[200:201], 11, v[240:241]
	v_lshl_add_u64 v[200:201], v[226:227], 0, v[200:201]
	global_load_dwordx4 v[138:141], v[200:201], off
	global_load_dwordx4 v[130:133], v[200:201], off offset:64
	v_lshlrev_b64 v[200:201], 11, v[234:235]
	v_lshl_add_u64 v[200:201], v[226:227], 0, v[200:201]
	global_load_dwordx4 v[118:121], v[200:201], off
	global_load_dwordx4 v[106:109], v[200:201], off offset:64
	v_lshlrev_b64 v[200:201], 11, v[230:231]
	v_lshl_add_u64 v[200:201], v[226:227], 0, v[200:201]
	global_load_dwordx4 v[102:105], v[200:201], off
	global_load_dwordx4 v[98:101], v[200:201], off offset:64
	s_waitcnt vmcnt(0)
	v_pk_mul_f32 v[246:247], v[246:247], s[64:65] op_sel_hi:[1,0]
	s_nop 0
	v_fma_f32 v247, -v246, v246, v247
	v_add_f32_e32 v247, 0x3727c5ac, v247
	v_mul_f32_e32 v236, 0x4b800000, v247
	v_cmp_gt_f32_e32 vcc, s29, v247
	v_mov_b32_e32 v178, v246
	s_nop 0
	v_cndmask_b32_e32 v247, v247, v236, vcc
	v_rsq_f32_e32 v247, v247
	s_nop 0
	v_mul_f32_e32 v236, 0x45800000, v247
	v_cndmask_b32_e32 v244, v247, v236, vcc
	v_pk_mul_f32 v[248:249], v[248:249], s[64:65] op_sel_hi:[1,0]
	s_nop 0
	v_fma_f32 v249, -v248, v248, v249
	v_add_f32_e32 v249, 0x3727c5ac, v249
	v_mul_f32_e32 v236, 0x4b800000, v249
	v_cmp_gt_f32_e32 vcc, s29, v249
	v_mov_b32_e32 v179, v248
	s_nop 0
	v_cndmask_b32_e32 v249, v249, v236, vcc
	v_rsq_f32_e32 v249, v249
	s_nop 0
	v_mul_f32_e32 v236, 0x45800000, v249
	v_cndmask_b32_e32 v242, v249, v236, vcc
	v_pk_mul_f32 v[250:251], v[250:251], s[64:65] op_sel_hi:[1,0]
	s_nop 0
	v_fma_f32 v251, -v250, v250, v251
	v_add_f32_e32 v251, 0x3727c5ac, v251
	v_mul_f32_e32 v236, 0x4b800000, v251
	v_cmp_gt_f32_e32 vcc, s29, v251
	v_mov_b32_e32 v180, v250
	s_nop 0
	v_cndmask_b32_e32 v251, v251, v236, vcc
	v_rsq_f32_e32 v251, v251
	s_nop 0
	v_mul_f32_e32 v236, 0x45800000, v251
	v_cndmask_b32_e32 v237, v251, v236, vcc
	v_pk_mul_f32 v[238:239], v[238:239], s[64:65] op_sel_hi:[1,0]
	s_nop 0
	v_fma_f32 v239, -v238, v238, v239
	v_add_f32_e32 v239, 0x3727c5ac, v239
	v_mul_f32_e32 v236, 0x4b800000, v239
	v_cmp_gt_f32_e32 vcc, s29, v239
	v_mov_b32_e32 v181, v238
	s_nop 0
	v_cndmask_b32_e32 v239, v239, v236, vcc
	v_rsq_f32_e32 v239, v239
	s_nop 0
	v_mul_f32_e32 v236, 0x45800000, v239
	v_cndmask_b32_e32 v232, v239, v236, vcc

;     __device__ __forceinline__ void operator()(const f32x4 (&acc)[2][2][4][2], const Unit& u, int wr, int wc, int fr, int fq) const {
;     ...
;             for (int m = 0; m < 4; ++m) {
;                 const int row = row0 + ai * HALF + m * 16; const size_t off = (size_t)row * 1024 + col0;
;                 ra[m] = 1.0f; rmu[m] = 0.0f;
;                 if (st) {
;                     const f32x2v sv = *(const f32x2v*)(st + 2 * (size_t)row); rmu[m] = sv.x * (1.0f / 1024.0f); ra[m] = rsqrtf(sv.y * (1.0f / 1024.0f) - rmu[m] * rmu[m] + 1e-5f);
;                     hv[m][0] = *(const f16x8*)(yh + off); hv[m][1] = *(const f16x8*)(yh + off + 32);
;                 }
;             }
.LBB0_915:
	s_and_b64 vcc, exec, s[38:39]
	s_cbranch_vccnz .Lres1_h2_skip
	v_add_u32_e32 v162, 0x80, v228
	v_ashrrev_i32_e32 v163, 31, v162
	v_lshl_add_u64 v[164:165], v[162:163], 3, s[80:81]
	global_load_dwordx2 v[166:167], v[164:165], off
	global_load_dwordx2 v[168:169], v[164:165], off offset:128
	global_load_dwordx2 v[170:171], v[164:165], off offset:256
	global_load_dwordx2 v[172:173], v[164:165], off offset:384
	v_add_u32_e32 v162, 0x80, v228
	v_ashrrev_i32_e32 v163, 31, v162
	v_lshlrev_b64 v[164:165], 11, v[162:163]
	v_lshl_add_u64 v[164:165], v[226:227], 0, v[164:165]
	global_load_dwordx4 v[158:161], v[164:165], off
	global_load_dwordx4 v[146:149], v[164:165], off offset:64
	v_add_u32_e32 v162, 0x90, v228
	v_ashrrev_i32_e32 v163, 31, v162
	v_lshlrev_b64 v[164:165], 11, v[162:163]
	v_lshl_add_u64 v[164:165], v[226:227], 0, v[164:165]
	global_load_dwordx4 v[138:141], v[164:165], off
	global_load_dwordx4 v[130:133], v[164:165], off offset:64
	v_add_u32_e32 v162, 0xa0, v228
	v_ashrrev_i32_e32 v163, 31, v162
	v_lshlrev_b64 v[164:165], 11, v[162:163]
	v_lshl_add_u64 v[164:165], v[226:227], 0, v[164:165]
	global_load_dwordx4 v[118:121], v[164:165], off
	global_load_dwordx4 v[106:109], v[164:165], off offset:64
	v_add_u32_e32 v162, 0xb0, v228
	v_ashrrev_i32_e32 v163, 31, v162
	v_lshlrev_b64 v[164:165], 11, v[162:163]
	v_lshl_add_u64 v[164:165], v[226:227], 0, v[164:165]
	global_load_dwordx4 v[102:105], v[164:165], off
	global_load_dwordx4 v[98:101], v[164:165], off offset:64

;     __device__ __forceinline__ void operator()(const f32x4 (&acc)[2][2][4][2], const Unit& u, int wr, int wc, int fr, int fq) const {
;     ...
;             for (int m = 0; m < 4; ++m) {
;                 const int row = row0 + ai * HALF + m * 16; const size_t off = (size_t)row * 1024 + col0;
;                 ra[m] = 1.0f; rmu[m] = 0.0f;
;                 if (st) {
;                     const f32x2v sv = *(const f32x2v*)(st + 2 * (size_t)row); rmu[m] = sv.x * (1.0f / 1024.0f); ra[m] = rsqrtf(sv.y * (1.0f / 1024.0f) - rmu[m] * rmu[m] + 1e-5f);
;                     hv[m][0] = *(const f16x8*)(yh + off); hv[m][1] = *(const f16x8*)(yh + off + 32);
;                 }
;             }
.LBB0_1144:
	v_lshl_add_u32 v228, s76, 8, v210
	v_lshl_add_u64 v[226:227], v[224:225], 1, s[92:93]
	v_ashrrev_i32_e32 v229, 31, v228
	v_or_b32_e32 v240, 16, v228
	v_ashrrev_i32_e32 v241, 31, v240
	v_or_b32_e32 v234, 32, v228
	v_ashrrev_i32_e32 v235, 31, v234
	v_or_b32_e32 v230, 48, v228
	v_ashrrev_i32_e32 v231, 31, v230
	v_mov_b32_e32 v242, 1.0
	v_mov_b32_e32 v244, 1.0
	v_mov_b32_e32 v237, 1.0
	v_mov_b32_e32 v232, 1.0
	v_mov_b32_e32 v178, 0
	v_mov_b32_e32 v179, s77
	v_mov_b32_e32 v180, s77
	v_mov_b32_e32 v181, s77
	s_and_b64 vcc, exec, s[38:39]
	s_cbranch_vccnz .Lres2_h1_nost
	v_lshl_add_u64 v[198:199], v[228:229], 3, s[86:87]
	global_load_dwordx2 v[246:247], v[198:199], off
	global_load_dwordx2 v[248:249], v[198:199], off offset:128
	global_load_dwordx2 v[250:251], v[198:199], off offset:256
	global_load_dwordx2 v[238:239], v[198:199], off offset:384
	v_lshlrev_b64 v[200:201], 11, v[228:229]
	v_lshl_add_u64 v[200:201], v[226:227], 0, v[200:201]
	global_load_dwordx4 v[158:161], v[200:201], off
	global_load_dwordx4 v[146:149], v[200:201], off offset:64
	v_lshlrev_b64 v[200:201], 11, v[240:241]
	v_lshl_add_u64 v[200:201], v[226:227], 0, v[200:201]
	global_load_dwordx4 v[138:141], v[200:201], off
	global_load_dwordx4 v[130:133], v[200:201], off offset:64
	v_lshlrev_b64 v[200:201], 11, v[234:235]
	v_lshl_add_u64 v[200:201], v[226:227], 0, v[200:201]
	global_load_dwordx4 v[118:121], v[200:201], off
	global_load_dwordx4 v[106:109], v[200:201], off offset:64
	v_lshlrev_b64 v[200:201], 11, v[230:231]
	v_lshl_add_u64 v[200:201], v[226:227], 0, v[200:201]
	global_load_dwordx4 v[102:105], v[200:201], off
	global_load_dwordx4 v[98:101], v[200:201], off offset:64
	s_waitcnt vmcnt(0)
	v_pk_mul_f32 v[246:247], v[246:247], s[64:65] op_sel_hi:[1,0]
	s_nop 0
	v_fma_f32 v247, -v246, v246, v247
	v_add_f32_e32 v247, 0x3727c5ac, v247
	v_mul_f32_e32 v236, 0x4b800000, v247
	v_cmp_gt_f32_e32 vcc, s29, v247
	v_mov_b32_e32 v178, v246
	s_nop 0
	v_cndmask_b32_e32 v247, v247, v236, vcc
	v_rsq_f32_e32 v247, v247
	s_nop 0
	v_mul_f32_e32 v236, 0x45800000, v247
	v_cndmask_b32_e32 v242, v247, v236, vcc
	v_pk_mul_f32 v[248:249], v[248:249], s[64:65] op_sel_hi:[1,0]
	s_nop 0
	v_fma_f32 v249, -v248, v248, v249
	v_add_f32_e32 v249, 0x3727c5ac, v249
	v_mul_f32_e32 v236, 0x4b800000, v249
	v_cmp_gt_f32_e32 vcc, s29, v249
	v_mov_b32_e32 v179, v248
	s_nop 0
	v_cndmask_b32_e32 v249, v249, v236, vcc
	v_rsq_f32_e32 v249, v249
	s_nop 0
	v_mul_f32_e32 v236, 0x45800000, v249
	v_cndmask_b32_e32 v244, v249, v236, vcc
	v_pk_mul_f32 v[250:251], v[250:251], s[64:65] op_sel_hi:[1,0]
	s_nop 0
	v_fma_f32 v251, -v250, v250, v251
	v_add_f32_e32 v251, 0x3727c5ac, v251
	v_mul_f32_e32 v236, 0x4b800000, v251
	v_cmp_gt_f32_e32 vcc, s29, v251
	v_mov_b32_e32 v180, v250
	s_nop 0
	v_cndmask_b32_e32 v251, v251, v236, vcc
	v_rsq_f32_e32 v251, v251
	s_nop 0
	v_mul_f32_e32 v236, 0x45800000, v251
	v_cndmask_b32_e32 v237, v251, v236, vcc
	v_pk_mul_f32 v[238:239], v[238:239], s[64:65] op_sel_hi:[1,0]
	s_nop 0
	v_fma_f32 v239, -v238, v238, v239
	v_add_f32_e32 v239, 0x3727c5ac, v239
	v_mul_f32_e32 v236, 0x4b800000, v239
	v_cmp_gt_f32_e32 vcc, s29, v239
	v_mov_b32_e32 v181, v238
	s_nop 0
	v_cndmask_b32_e32 v239, v239, v236, vcc
	v_rsq_f32_e32 v239, v239
	s_nop 0
	v_mul_f32_e32 v236, 0x45800000, v239
	v_cndmask_b32_e32 v232, v239, v236, vcc

;     __device__ __forceinline__ void operator()(const f32x4 (&acc)[2][2][4][2], const Unit& u, int wr, int wc, int fr, int fq) const {
;     ...
;             for (int m = 0; m < 4; ++m) {
;                 const int row = row0 + ai * HALF + m * 16; const size_t off = (size_t)row * 1024 + col0;
;                 ra[m] = 1.0f; rmu[m] = 0.0f;
;                 if (st) {
;                     const f32x2v sv = *(const f32x2v*)(st + 2 * (size_t)row); rmu[m] = sv.x * (1.0f / 1024.0f); ra[m] = rsqrtf(sv.y * (1.0f / 1024.0f) - rmu[m] * rmu[m] + 1e-5f);
;                     hv[m][0] = *(const f16x8*)(yh + off); hv[m][1] = *(const f16x8*)(yh + off + 32);
;                 }
;             }
.LBB0_1189:
	s_and_b64 vcc, exec, s[38:39]
	s_cbranch_vccnz .Lres2_h2_skip
	v_add_u32_e32 v162, 0x80, v228
	v_ashrrev_i32_e32 v163, 31, v162
	v_lshl_add_u64 v[164:165], v[162:163], 3, s[86:87]
	global_load_dwordx2 v[166:167], v[164:165], off
	global_load_dwordx2 v[168:169], v[164:165], off offset:128
	global_load_dwordx2 v[170:171], v[164:165], off offset:256
	global_load_dwordx2 v[172:173], v[164:165], off offset:384
	v_add_u32_e32 v162, 0x80, v228
	v_ashrrev_i32_e32 v163, 31, v162
	v_lshlrev_b64 v[164:165], 11, v[162:163]
	v_lshl_add_u64 v[164:165], v[226:227], 0, v[164:165]
	global_load_dwordx4 v[158:161], v[164:165], off
	global_load_dwordx4 v[146:149], v[164:165], off offset:64
	v_add_u32_e32 v162, 0x90, v228
	v_ashrrev_i32_e32 v163, 31, v162
	v_lshlrev_b64 v[164:165], 11, v[162:163]
	v_lshl_add_u64 v[164:165], v[226:227], 0, v[164:165]
	global_load_dwordx4 v[138:141], v[164:165], off
	global_load_dwordx4 v[130:133], v[164:165], off offset:64
	v_add_u32_e32 v162, 0xa0, v228
	v_ashrrev_i32_e32 v163, 31, v162
	v_lshlrev_b64 v[164:165], 11, v[162:163]
	v_lshl_add_u64 v[164:165], v[226:227], 0, v[164:165]
	global_load_dwordx4 v[118:121], v[164:165], off
	global_load_dwordx4 v[106:109], v[164:165], off offset:64
	v_add_u32_e32 v162, 0xb0, v228
	v_ashrrev_i32_e32 v163, 31, v162
	v_lshlrev_b64 v[164:165], 11, v[162:163]
	v_lshl_add_u64 v[164:165], v[226:227], 0, v[164:165]
	global_load_dwordx4 v[102:105], v[164:165], off
	global_load_dwordx4 v[98:101], v[164:165], off offset:64
